# P9 K-loop: LDS-DMA staging rebalanced 4/4 between the two load segments (As[b][0] staged one segment later), waits recounted
# speedup vs baseline: 1.0050x; 1.0050x over previous
.LBB0_1019:
	ds_read_b128 v[16:19], v183
	ds_read_b128 v[20:23], v183 offset:1024
	ds_read_b128 v[24:27], v183 offset:2048
	ds_read_b128 v[28:31], v183 offset:3072
	ds_read_b128 v[0:3], v184
	ds_read_b128 v[4:7], v184 offset:1024
	ds_read_b128 v[8:11], v184 offset:2048
	ds_read_b128 v[12:15], v184 offset:3072
	s_add_u32 s38, s36, 0xffe00080
	s_addc_u32 s39, s37, -1
	s_cmpk_eq_i32 s60, 0x7c
	s_cselect_b32 s41, s25, s39
	s_cselect_b32 s40, s56, s38
	s_cselect_b32 s39, s23, s59
	s_cselect_b32 s38, s57, s58
	s_add_u32 s62, s36, 0xffe00000
	s_addc_u32 s63, s37, -1
	v_lshl_add_u64 v[212:213], s[62:63], 0, v[164:165]
	s_mov_b32 m0, s51
	ds_read_b128 v[172:175], v185
	ds_read_b128 v[176:179], v185 offset:1024
	ds_read_b128 v[188:191], v185 offset:2048
	ds_read_b128 v[192:195], v185 offset:3072
	ds_read_b128 v[196:199], v185 offset:4096
	ds_read_b128 v[200:203], v185 offset:5120
	ds_read_b128 v[204:207], v185 offset:6144
	ds_read_b128 v[208:211], v185 offset:7168
	global_load_lds_dwordx4 v[212:213], off
	v_lshl_add_u64 v[212:213], s[62:63], 0, v[166:167]
	s_mov_b32 m0, s52
	s_nop 0
	global_load_lds_dwordx4 v[212:213], off
	v_lshl_add_u64 v[212:213], s[36:37], 0, v[164:165]
	s_add_i32 m0, s31, 0xc000
	s_nop 0
	global_load_lds_dwordx4 v[212:213], off
	v_lshl_add_u64 v[212:213], s[36:37], 0, v[166:167]
	s_add_i32 m0, s31, 0xe000
	s_nop 0
	global_load_lds_dwordx4 v[212:213], off
	s_waitcnt vmcnt(8)
	s_waitcnt lgkmcnt(0)
	s_barrier
	s_setprio 1
	s_waitcnt lgkmcnt(0)
	s_nop 1
	v_mfma_scale_f32_16x16x128_f8f6f4 v[156:159], v[16:23], v[172:179], v[156:159], v186, v186 op_sel_hi:[0,0,0]
	s_nop 1
	v_mfma_scale_f32_16x16x128_f8f6f4 v[152:155], v[24:31], v[172:179], v[152:155], v186, v186 op_sel_hi:[0,0,0]
	s_nop 1
	v_mfma_scale_f32_16x16x128_f8f6f4 v[148:151], v[16:23], v[188:195], v[148:151], v186, v186 op_sel_hi:[0,0,0]
	s_nop 1
	v_mfma_scale_f32_16x16x128_f8f6f4 v[144:147], v[24:31], v[188:195], v[144:147], v186, v186 op_sel_hi:[0,0,0]
	s_nop 1
	v_mfma_scale_f32_16x16x128_f8f6f4 v[140:143], v[16:23], v[196:203], v[140:143], v186, v186 op_sel_hi:[0,0,0]
	s_nop 1
	v_mfma_scale_f32_16x16x128_f8f6f4 v[124:127], v[24:31], v[196:203], v[124:127], v186, v186 op_sel_hi:[0,0,0]
	s_nop 1
	v_mfma_scale_f32_16x16x128_f8f6f4 v[116:119], v[16:23], v[204:211], v[116:119], v186, v186 op_sel_hi:[0,0,0]
	s_nop 1
	v_mfma_scale_f32_16x16x128_f8f6f4 v[108:111], v[24:31], v[204:211], v[108:111], v186, v186 op_sel_hi:[0,0,0]
	s_setprio 0
	s_setprio 1
	s_nop 1
	v_mfma_scale_f32_16x16x128_f8f6f4 v[136:139], v[0:7], v[172:179], v[136:139], v186, v186 op_sel_hi:[0,0,0]
	s_nop 1
	v_mfma_scale_f32_16x16x128_f8f6f4 v[132:135], v[8:15], v[172:179], v[132:135], v186, v186 op_sel_hi:[0,0,0]
	s_nop 1
	v_mfma_scale_f32_16x16x128_f8f6f4 v[128:131], v[0:7], v[188:195], v[128:131], v186, v186 op_sel_hi:[0,0,0]
	s_nop 1
	v_mfma_scale_f32_16x16x128_f8f6f4 v[120:123], v[8:15], v[188:195], v[120:123], v186, v186 op_sel_hi:[0,0,0]
	s_nop 1
	v_mfma_scale_f32_16x16x128_f8f6f4 v[112:115], v[0:7], v[196:203], v[112:115], v186, v186 op_sel_hi:[0,0,0]
	s_nop 1
	v_mfma_scale_f32_16x16x128_f8f6f4 v[104:107], v[8:15], v[196:203], v[104:107], v186, v186 op_sel_hi:[0,0,0]
	s_nop 1
	v_mfma_scale_f32_16x16x128_f8f6f4 v[100:103], v[0:7], v[204:211], v[100:103], v186, v186 op_sel_hi:[0,0,0]
	s_nop 1
	v_mfma_scale_f32_16x16x128_f8f6f4 v[96:99], v[8:15], v[204:211], v[96:99], v186, v186 op_sel_hi:[0,0,0]
	s_setprio 0
	s_barrier
	s_add_i32 s61, s53, s42
	v_lshl_add_u64 v[172:173], s[38:39], 0, v[162:163]
	s_mov_b32 m0, s61
	ds_read_b128 v[188:191], v185 offset:16384
	ds_read_b128 v[192:195], v185 offset:17408
	ds_read_b128 v[196:199], v185 offset:18432
	ds_read_b128 v[200:203], v185 offset:19456
	ds_read_b128 v[204:207], v185 offset:20480
	ds_read_b128 v[208:211], v185 offset:21504
	ds_read_b128 v[212:215], v185 offset:22528
	ds_read_b128 v[216:219], v185 offset:23552
	global_load_lds_dwordx4 v[172:173], off
	s_add_i32 m0, s61, 0x2000
	s_add_u32 s62, s38, 0x200000
	v_lshl_add_u64 v[174:175], s[38:39], 0, v[160:161]
	s_addc_u32 s63, s39, 0
	s_add_i32 s61, s54, s42
	global_load_lds_dwordx4 v[174:175], off
	v_lshl_add_u64 v[176:177], s[62:63], 0, v[162:163]
	s_mov_b32 m0, s61
	v_lshl_add_u64 v[178:179], s[40:41], 0, v[160:161]
	global_load_lds_dwordx4 v[176:177], off
	v_lshl_add_u64 v[176:177], s[62:63], 0, v[160:161]
	s_add_i32 m0, s61, 0x2000
	s_nop 0
	global_load_lds_dwordx4 v[176:177], off
	v_lshl_add_u64 v[176:177], s[40:41], 0, v[162:163]
	s_waitcnt vmcnt(6)
	s_waitcnt lgkmcnt(0)
	s_barrier
	s_setprio 1
	s_waitcnt lgkmcnt(0)
	s_nop 1
	v_mfma_scale_f32_16x16x128_f8f6f4 v[92:95], v[16:23], v[188:195], v[92:95], v186, v186 op_sel_hi:[0,0,0]
	s_nop 1
	v_mfma_scale_f32_16x16x128_f8f6f4 v[88:91], v[24:31], v[188:195], v[88:91], v186, v186 op_sel_hi:[0,0,0]
	s_nop 1
	v_mfma_scale_f32_16x16x128_f8f6f4 v[84:87], v[16:23], v[196:203], v[84:87], v186, v186 op_sel_hi:[0,0,0]
	s_nop 1
	v_mfma_scale_f32_16x16x128_f8f6f4 v[80:83], v[24:31], v[196:203], v[80:83], v186, v186 op_sel_hi:[0,0,0]
	s_nop 1
	v_mfma_scale_f32_16x16x128_f8f6f4 v[76:79], v[16:23], v[204:211], v[76:79], v186, v186 op_sel_hi:[0,0,0]
	s_nop 1
	v_mfma_scale_f32_16x16x128_f8f6f4 v[64:67], v[24:31], v[204:211], v[64:67], v186, v186 op_sel_hi:[0,0,0]
	s_nop 1
	v_mfma_scale_f32_16x16x128_f8f6f4 v[52:55], v[16:23], v[212:219], v[52:55], v186, v186 op_sel_hi:[0,0,0]
	s_nop 1
	v_mfma_scale_f32_16x16x128_f8f6f4 v[44:47], v[24:31], v[212:219], v[44:47], v186, v186 op_sel_hi:[0,0,0]
	s_setprio 0
	s_setprio 1
	s_nop 1
	v_mfma_scale_f32_16x16x128_f8f6f4 v[72:75], v[0:7], v[188:195], v[72:75], v186, v186 op_sel_hi:[0,0,0]
	s_nop 1
	v_mfma_scale_f32_16x16x128_f8f6f4 v[68:71], v[8:15], v[188:195], v[68:71], v186, v186 op_sel_hi:[0,0,0]
	s_nop 1
	v_mfma_scale_f32_16x16x128_f8f6f4 v[60:63], v[0:7], v[196:203], v[60:63], v186, v186 op_sel_hi:[0,0,0]
	s_nop 1
	v_mfma_scale_f32_16x16x128_f8f6f4 v[56:59], v[8:15], v[196:203], v[56:59], v186, v186 op_sel_hi:[0,0,0]
	s_nop 1
	v_mfma_scale_f32_16x16x128_f8f6f4 v[48:51], v[0:7], v[204:211], v[48:51], v186, v186 op_sel_hi:[0,0,0]
	s_nop 1
	v_mfma_scale_f32_16x16x128_f8f6f4 v[40:43], v[8:15], v[204:211], v[40:43], v186, v186 op_sel_hi:[0,0,0]
	s_nop 1
	v_mfma_scale_f32_16x16x128_f8f6f4 v[36:39], v[0:7], v[212:219], v[36:39], v186, v186 op_sel_hi:[0,0,0]
	s_nop 1
	v_mfma_scale_f32_16x16x128_f8f6f4 v[32:35], v[8:15], v[212:219], v[32:35], v186, v186 op_sel_hi:[0,0,0]
	s_setprio 0
	s_barrier
	s_add_i32 s61, 0, 0x18000
	s_add_i32 s62, 0, 0x1c000
	v_add_u32_e32 v12, s61, v181
	v_add_u32_e32 v28, s62, v181
	ds_read_b128 v[0:3], v12
	ds_read_b128 v[4:7], v12 offset:1024
	ds_read_b128 v[8:11], v12 offset:2048
	ds_read_b128 v[12:15], v12 offset:3072
	ds_read_b128 v[16:19], v28
	ds_read_b128 v[20:23], v28 offset:1024
	ds_read_b128 v[24:27], v28 offset:2048
	ds_read_b128 v[28:31], v28 offset:3072
	s_add_u32 s40, s40, 0x200000
	s_addc_u32 s41, s41, 0
	s_mov_b32 m0, s31
	v_lshl_add_u64 v[220:221], s[40:41], 0, v[162:163]
	ds_read_b128 v[188:191], v185 offset:32768
	ds_read_b128 v[192:195], v185 offset:33792
	ds_read_b128 v[196:199], v185 offset:34816
	ds_read_b128 v[200:203], v185 offset:35840
	ds_read_b128 v[204:207], v185 offset:36864
	ds_read_b128 v[208:211], v185 offset:37888
	ds_read_b128 v[212:215], v185 offset:38912
	ds_read_b128 v[216:219], v185 offset:39936
	global_load_lds_dwordx4 v[176:177], off
	s_mov_b32 m0, s44
	s_nop 0
	global_load_lds_dwordx4 v[178:179], off
	s_mov_b32 m0, s45
	s_nop 0
	global_load_lds_dwordx4 v[220:221], off
	v_lshl_add_u64 v[220:221], s[40:41], 0, v[160:161]
	s_mov_b32 m0, s46
	s_nop 0
	global_load_lds_dwordx4 v[220:221], off
	s_waitcnt vmcnt(8)
	s_waitcnt lgkmcnt(0)
	s_barrier
	s_setprio 1
	s_waitcnt lgkmcnt(0)
	s_nop 1
	v_mfma_scale_f32_16x16x128_f8f6f4 v[156:159], v[0:7], v[188:195], v[156:159], v186, v186 op_sel_hi:[0,0,0]
	s_nop 1
	v_mfma_scale_f32_16x16x128_f8f6f4 v[152:155], v[8:15], v[188:195], v[152:155], v186, v186 op_sel_hi:[0,0,0]
	s_nop 1
	v_mfma_scale_f32_16x16x128_f8f6f4 v[148:151], v[0:7], v[196:203], v[148:151], v186, v186 op_sel_hi:[0,0,0]
	s_nop 1
	v_mfma_scale_f32_16x16x128_f8f6f4 v[144:147], v[8:15], v[196:203], v[144:147], v186, v186 op_sel_hi:[0,0,0]
	s_nop 1
	v_mfma_scale_f32_16x16x128_f8f6f4 v[140:143], v[0:7], v[204:211], v[140:143], v186, v186 op_sel_hi:[0,0,0]
	s_nop 1
	v_mfma_scale_f32_16x16x128_f8f6f4 v[124:127], v[8:15], v[204:211], v[124:127], v186, v186 op_sel_hi:[0,0,0]
	s_nop 1
	v_mfma_scale_f32_16x16x128_f8f6f4 v[116:119], v[0:7], v[212:219], v[116:119], v186, v186 op_sel_hi:[0,0,0]
	s_nop 1
	v_mfma_scale_f32_16x16x128_f8f6f4 v[108:111], v[8:15], v[212:219], v[108:111], v186, v186 op_sel_hi:[0,0,0]
	s_setprio 0
	s_setprio 1
	s_nop 1
	v_mfma_scale_f32_16x16x128_f8f6f4 v[136:139], v[16:23], v[188:195], v[136:139], v186, v186 op_sel_hi:[0,0,0]
	s_nop 1
	v_mfma_scale_f32_16x16x128_f8f6f4 v[132:135], v[24:31], v[188:195], v[132:135], v186, v186 op_sel_hi:[0,0,0]
	s_nop 1
	v_mfma_scale_f32_16x16x128_f8f6f4 v[128:131], v[16:23], v[196:203], v[128:131], v186, v186 op_sel_hi:[0,0,0]
	s_nop 1
	v_mfma_scale_f32_16x16x128_f8f6f4 v[120:123], v[24:31], v[196:203], v[120:123], v186, v186 op_sel_hi:[0,0,0]
	s_nop 1
	v_mfma_scale_f32_16x16x128_f8f6f4 v[112:115], v[16:23], v[204:211], v[112:115], v186, v186 op_sel_hi:[0,0,0]
	s_nop 1
	v_mfma_scale_f32_16x16x128_f8f6f4 v[104:107], v[24:31], v[204:211], v[104:107], v186, v186 op_sel_hi:[0,0,0]
	s_nop 1
	v_mfma_scale_f32_16x16x128_f8f6f4 v[100:103], v[16:23], v[212:219], v[100:103], v186, v186 op_sel_hi:[0,0,0]
	s_nop 1
	v_mfma_scale_f32_16x16x128_f8f6f4 v[96:99], v[24:31], v[212:219], v[96:99], v186, v186 op_sel_hi:[0,0,0]
	s_setprio 0
	s_barrier
	s_add_i32 s40, s61, s42
	v_lshl_add_u64 v[172:173], v[172:173], 0, s[6:7]
	s_mov_b32 m0, s40
	ds_read_b128 v[188:191], v185 offset:49152
	ds_read_b128 v[192:195], v185 offset:50176
	ds_read_b128 v[196:199], v185 offset:51200
	ds_read_b128 v[200:203], v185 offset:52224
	ds_read_b128 v[204:207], v185 offset:53248
	ds_read_b128 v[208:211], v185 offset:54272
	ds_read_b128 v[212:215], v185 offset:55296
	ds_read_b128 v[216:219], v185 offset:56320
	global_load_lds_dwordx4 v[172:173], off
	s_add_i32 m0, s40, 0x2000
	s_add_u32 s38, s38, 0x200080
	v_lshl_add_u64 v[172:173], v[174:175], 0, s[6:7]
	s_addc_u32 s39, s39, 0
	s_add_i32 s40, s62, s42
	global_load_lds_dwordx4 v[172:173], off
	v_lshl_add_u64 v[172:173], s[38:39], 0, v[162:163]
	s_mov_b32 m0, s40
	s_nop 0
	global_load_lds_dwordx4 v[172:173], off
	v_lshl_add_u64 v[172:173], s[38:39], 0, v[160:161]
	s_add_i32 m0, s40, 0x2000
	s_nop 0
	global_load_lds_dwordx4 v[172:173], off
	s_waitcnt vmcnt(6)
	s_waitcnt lgkmcnt(0)
	s_barrier
	s_setprio 1
	s_waitcnt lgkmcnt(0)
	s_nop 1
	v_mfma_scale_f32_16x16x128_f8f6f4 v[92:95], v[0:7], v[188:195], v[92:95], v186, v186 op_sel_hi:[0,0,0]
	s_nop 1
	v_mfma_scale_f32_16x16x128_f8f6f4 v[88:91], v[8:15], v[188:195], v[88:91], v186, v186 op_sel_hi:[0,0,0]
	s_nop 1
	v_mfma_scale_f32_16x16x128_f8f6f4 v[84:87], v[0:7], v[196:203], v[84:87], v186, v186 op_sel_hi:[0,0,0]
	s_nop 1
	v_mfma_scale_f32_16x16x128_f8f6f4 v[80:83], v[8:15], v[196:203], v[80:83], v186, v186 op_sel_hi:[0,0,0]
	s_nop 1
	v_mfma_scale_f32_16x16x128_f8f6f4 v[76:79], v[0:7], v[204:211], v[76:79], v186, v186 op_sel_hi:[0,0,0]
	s_nop 1
	v_mfma_scale_f32_16x16x128_f8f6f4 v[64:67], v[8:15], v[204:211], v[64:67], v186, v186 op_sel_hi:[0,0,0]
	s_nop 1
	v_mfma_scale_f32_16x16x128_f8f6f4 v[52:55], v[0:7], v[212:219], v[52:55], v186, v186 op_sel_hi:[0,0,0]
	s_nop 1
	v_mfma_scale_f32_16x16x128_f8f6f4 v[44:47], v[8:15], v[212:219], v[44:47], v186, v186 op_sel_hi:[0,0,0]
	s_setprio 0
	s_setprio 1
	s_nop 1
	v_mfma_scale_f32_16x16x128_f8f6f4 v[72:75], v[16:23], v[188:195], v[72:75], v186, v186 op_sel_hi:[0,0,0]
	s_nop 1
	v_mfma_scale_f32_16x16x128_f8f6f4 v[68:71], v[24:31], v[188:195], v[68:71], v186, v186 op_sel_hi:[0,0,0]
	s_nop 1
	v_mfma_scale_f32_16x16x128_f8f6f4 v[60:63], v[16:23], v[196:203], v[60:63], v186, v186 op_sel_hi:[0,0,0]
	s_nop 1
	v_mfma_scale_f32_16x16x128_f8f6f4 v[56:59], v[24:31], v[196:203], v[56:59], v186, v186 op_sel_hi:[0,0,0]
	s_nop 1
	v_mfma_scale_f32_16x16x128_f8f6f4 v[48:51], v[16:23], v[204:211], v[48:51], v186, v186 op_sel_hi:[0,0,0]
	s_nop 1
	v_mfma_scale_f32_16x16x128_f8f6f4 v[40:43], v[24:31], v[204:211], v[40:43], v186, v186 op_sel_hi:[0,0,0]
	s_nop 1
	v_mfma_scale_f32_16x16x128_f8f6f4 v[36:39], v[16:23], v[212:219], v[36:39], v186, v186 op_sel_hi:[0,0,0]
	s_nop 1
	v_mfma_scale_f32_16x16x128_f8f6f4 v[32:35], v[24:31], v[212:219], v[32:35], v186, v186 op_sel_hi:[0,0,0]
	s_setprio 0
	s_barrier
	s_add_i32 s60, s60, 2
	s_add_u32 s36, s36, 0x100
	s_addc_u32 s37, s37, 0
	s_add_u32 s58, s58, 0x100
	s_addc_u32 s59, s59, 0
	s_cmpk_lt_u32 s60, 0x7e
	s_cbranch_scc1 .LBB0_1019
	s_nop 15
	s_nop 15
	s_andn2_b64 vcc, exec, s[12:13]
	s_cbranch_vccnz .LBB0_1022
	s_barrier
